# dn GEMM (bf16 residual path): residual epilogue rewritten by hand - all 16 residual-tile loads issued up front into the free fragment registers (one memory latency per tile instead of eight serial one
# baseline (speedup 1.0000x reference)
;     __device__ __forceinline__ void operator()(const f32x4 (&acc)[2][2][4][2], const Unit& u, int ui, int wr, int wc, int fr, int fq) const {
;     ...
;             for (int m = 0; m < 4; ++m) { const int row = row0 + ai * HALF + m * 16; const size_t off = (size_t)row * 1024 + col0; float q = 0.f;
;                 f32x4 v[2][2];
;                 if (basef) {
; #pragma unroll
;                     for (int bj = 0; bj < 2; ++bj) { v[bj][0] = *(const f32x4*)(basef + off + bj * HALF); v[bj][1] = *(const f32x4*)(basef + off + bj * HALF + 4); }
;                 } else {
; #pragma unroll
;                     for (int bj = 0; bj < 2; ++bj) { const u32x4 raw = *(const u32x4*)(xb + off + bj * HALF);
;                         v[bj][0] = (f32x4){__builtin_bit_cast(float, raw.x << 16), __builtin_bit_cast(float, raw.x & 0xffff0000u), __builtin_bit_cast(float, raw.y << 16), __builtin_bit_cast(float, raw.y & 0xffff0000u)};
;                         v[bj][1] = (f32x4){__builtin_bit_cast(float, raw.z << 16), __builtin_bit_cast(float, raw.z & 0xffff0000u), __builtin_bit_cast(float, raw.w << 16), __builtin_bit_cast(float, raw.w & 0xffff0000u)}; }
;                 }
.LBB0_548:
	s_and_b64 vcc, exec, s[24:25]
	s_cbranch_vccz .Ldn_epi_fast
	s_lshl_b32 s0, s12, 8
	v_mov_b32_e32 v183, v147
	v_mov_b32_e32 v128, v180
	s_add_i32 s0, s0, s45
	v_cndmask_b32_e64 v130, 0, 1, s[24:25]
	v_add_u32_e32 v176, s0, v128
	s_lshl_b32 s0, s56, 8
	s_or_b32 s0, s0, s46
	v_lshl_add_u32 v174, v183, 3, s0
	v_ashrrev_i32_e32 v177, 31, v176
	v_ashrrev_i32_e32 v175, 31, v174
	v_lshlrev_b64 v[128:129], 10, v[176:177]
	v_cmp_ne_u32_e64 s[12:13], 1, v130
	s_andn2_b64 vcc, exec, s[24:25]
	v_lshl_add_u64 v[178:179], v[128:129], 0, v[174:175]
	s_cbranch_vccnz .LBB0_591
	v_lshl_add_u64 v[128:129], v[178:179], 2, s[14:15]
	global_load_dwordx4 v[140:143], v[128:129], off
	global_load_dwordx4 v[136:139], v[128:129], off offset:16
	global_load_dwordx4 v[132:135], v[128:129], off offset:512
	s_nop 0
	global_load_dwordx4 v[128:131], v[128:129], off offset:528
	v_lshl_add_u64 v[178:179], v[178:179], 1, s[18:19]
	s_cbranch_execnz .LBB0_551

; #define PG8_BAR __builtin_amdgcn_s_barrier()
; template <class Epi, class Sched, bool ALIGN_EPI = false, bool SP2 = false>
; __device__ __forceinline__ void gemm_phase(PG8_LAS unsigned char* lds, const Gemm g, const Sched& S, const Epi& E) {
;     ...
;         if (!has_next) break;
; #pragma unroll
;         for (int a = 0; a < 2; ++a)
; #pragma unroll
;             for (int b = 0; b < 2; ++b)
; #pragma unroll
;                 for (int m = 0; m < 4; ++m)
; #pragma unroll
;                     for (int n = 0; n < 2; ++n) acc[a][b][m][n] = (f32x4){0.f, 0.f, 0.f, 0.f};
;         cur = nxt; cA = nA; cB = nB; ++ui;
;         if constexpr (ALIGN_EPI) { if (wr == 1) PG8_BAR; }
.Ldn_epi_done:
	s_and_b64 vcc, exec, s[8:9]
	s_mov_b64 s[0:1], -1
	s_cbranch_vccnz .LBB0_533
	s_andn2_b64 vcc, exec, s[16:17]
	s_cbranch_vccnz .LBB0_532
	s_barrier
	s_branch .LBB0_532

;     __device__ __forceinline__ void operator()(const f32x4 (&acc)[2][2][4][2], const Unit& u, int ui, int wr, int wc, int fr, int fq) const {
;     ...
;         const int row0 = u.pm * BM + wr * 64 + fr, col0 = u.pn * BM + wc * 32 + 8 * fq;
;         f32x4 bv[2][2];
; #pragma unroll
;         for (int bj = 0; bj < 2; ++bj)
; #pragma unroll
;             for (int n = 0; n < 2; ++n) bv[bj][n] = HAS_BIAS ? *(const f32x4*)(bias + col0 + bj * HALF + 4 * n) : (f32x4){0.f, 0.f, 0.f, 0.f};
; #pragma unroll
;         for (int ai = 0; ai < 2; ++ai)
; #pragma unroll
;             for (int m = 0; m < 4; ++m) { const int row = row0 + ai * HALF + m * 16; const size_t off = (size_t)row * 1024 + col0; float q = 0.f;
;                 f32x4 v[2][2];
;                 if (basef) {
; #pragma unroll
;                     for (int bj = 0; bj < 2; ++bj) { v[bj][0] = *(const f32x4*)(basef + off + bj * HALF); v[bj][1] = *(const f32x4*)(basef + off + bj * HALF + 4); }
;                 } else {
; #pragma unroll
;                     for (int bj = 0; bj < 2; ++bj) { const u32x4 raw = *(const u32x4*)(xb + off + bj * HALF);
;                         v[bj][0] = (f32x4){__builtin_bit_cast(float, raw.x << 16), __builtin_bit_cast(float, raw.x & 0xffff0000u), __builtin_bit_cast(float, raw.y << 16), __builtin_bit_cast(float, raw.y & 0xffff0000u)};
;                         v[bj][1] = (f32x4){__builtin_bit_cast(float, raw.z << 16), __builtin_bit_cast(float, raw.z & 0xffff0000u), __builtin_bit_cast(float, raw.w << 16), __builtin_bit_cast(float, raw.w & 0xffff0000u)}; }
;                 }
; #pragma unroll
;                 for (int bj = 0; bj < 2; ++bj) {
;                     f32x4 v0 = v[bj][0] + acc[ai][bj][m][0] * alpha, v1 = v[bj][1] + acc[ai][bj][m][1] * alpha;
;                     if (HAS_BIAS) { v0 += bv[bj][0]; v1 += bv[bj][1]; }
;                     if (outf) { *(f32x4*)(outf + off + bj * HALF) = v0; *(f32x4*)(outf + off + bj * HALF + 4) = v1; }
;                     else *(u32x4*)(xb + off + bj * HALF) = pack8(v0, v1);
;                     q += (v0[0] * v0[0] + v0[1] * v0[1]) + (v0[2] * v0[2] + v0[3] * v0[3]) + (v1[0] * v1[0] + v1[1] * v1[1]) + (v1[2] * v1[2] + v1[3] * v1[3]); }
;                 q += __shfl_xor(q, 16); q += __shfl_xor(q, 32);
;                 if (fq == 0) ssp[(size_t)row * 16 + u.pn * 4 + wc] = q;
.Ldn_epi_fast:
	v_lshlrev_b32_e32 v178, 11, v180
	v_lshl_add_u32 v178, v147, 4, v178
	v_lshlrev_b32_e32 v179, 6, v180
	v_xor_b32_e32 v183, 16, v192
	v_lshlrev_b32_e32 v183, 2, v183
	v_xor_b32_e32 v228, 32, v192
	v_lshlrev_b32_e32 v228, 2, v228
	s_lshl_b32 s4, s12, 8
	s_add_i32 s4, s4, s45
	s_lshl_b32 s6, s56, 8
	s_add_i32 s6, s6, s46
	s_lshl_b32 s7, s6, 1
	s_mov_b32 s5, 0
	s_lshl_b64 s[0:1], s[4:5], 11
	s_add_u32 s0, s0, s7
	s_addc_u32 s1, s1, 0
	s_add_u32 s0, s0, s18
	s_addc_u32 s1, s1, s19
	s_mov_b64 s[98:99], s[0:1]
	s_lshl_b64 s[2:3], s[4:5], 6
	s_lshl_b32 s7, s56, 4
	s_add_u32 s2, s2, s7
	s_addc_u32 s3, s3, 0
	s_lshl_b32 s7, s44, 2
	s_add_u32 s2, s2, s7
	s_addc_u32 s3, s3, 0
	s_add_u32 s2, s2, s20
	s_addc_u32 s3, s3, s21
	s_mov_b32 s5, 0xffff0000
	global_load_dwordx4 v[128:131], v178, s[0:1]
	global_load_dwordx4 v[132:135], v178, s[0:1] offset:256
	s_add_u32 s0, s0, 0x8000
	s_addc_u32 s1, s1, 0
	global_load_dwordx4 v[136:139], v178, s[0:1]
	global_load_dwordx4 v[140:143], v178, s[0:1] offset:256
	s_add_u32 s0, s0, 0x8000
	s_addc_u32 s1, s1, 0
	global_load_dwordx4 v[174:177], v178, s[0:1]
	global_load_dwordx4 v[184:187], v178, s[0:1] offset:256
	s_add_u32 s0, s0, 0x8000
	s_addc_u32 s1, s1, 0
	global_load_dwordx4 v[188:191], v178, s[0:1]
	global_load_dwordx4 v[208:211], v178, s[0:1] offset:256
	s_add_u32 s0, s0, 0x28000
	s_addc_u32 s1, s1, 0
	global_load_dwordx4 v[212:215], v178, s[0:1]
	global_load_dwordx4 v[216:219], v178, s[0:1] offset:256
	s_add_u32 s0, s0, 0x8000
	s_addc_u32 s1, s1, 0
	global_load_dwordx4 v[220:223], v178, s[0:1]
	global_load_dwordx4 v[224:227], v178, s[0:1] offset:256
	s_add_u32 s0, s0, 0x8000
	s_addc_u32 s1, s1, 0
	global_load_dwordx4 v[230:233], v178, s[0:1]
	global_load_dwordx4 v[234:237], v178, s[0:1] offset:256
	s_add_u32 s0, s0, 0x8000
	s_addc_u32 s1, s1, 0
	global_load_dwordx4 v[238:241], v178, s[0:1]
	global_load_dwordx4 v[242:245], v178, s[0:1] offset:256
	s_mov_b64 s[0:1], s[98:99]
	s_waitcnt vmcnt(14)
	v_lshlrev_b32_e32 v246, 16, v128
	v_and_b32_e32 v128, s5, v128
	v_lshlrev_b32_e32 v247, 16, v129
	v_and_b32_e32 v129, s5, v129
	v_lshlrev_b32_e32 v248, 16, v130
	v_and_b32_e32 v130, s5, v130
	v_lshlrev_b32_e32 v249, 16, v131
	v_and_b32_e32 v131, s5, v131
	v_fma_f32 v124, v124, 0.5, v246
	v_fma_f32 v125, v125, 0.5, v128
	v_fma_f32 v126, v126, 0.5, v247
	v_fma_f32 v127, v127, 0.5, v129
	v_fma_f32 v120, v120, 0.5, v248
	v_fma_f32 v121, v121, 0.5, v130
	v_fma_f32 v122, v122, 0.5, v249
	v_fma_f32 v123, v123, 0.5, v131
	v_cvt_pk_bf16_f32 v128, v124, v125
	v_cvt_pk_bf16_f32 v129, v126, v127
	v_cvt_pk_bf16_f32 v130, v120, v121
	v_cvt_pk_bf16_f32 v131, v122, v123
	v_mul_f32_e32 v124, v124, v124
	v_fmac_f32_e32 v124, v125, v125
	v_fmac_f32_e32 v124, v126, v126
	v_fmac_f32_e32 v124, v127, v127
	v_fmac_f32_e32 v124, v120, v120
	v_fmac_f32_e32 v124, v121, v121
	v_fmac_f32_e32 v124, v122, v122
	v_fmac_f32_e32 v124, v123, v123
	v_lshlrev_b32_e32 v246, 16, v132
	v_and_b32_e32 v132, s5, v132
	v_lshlrev_b32_e32 v247, 16, v133
	v_and_b32_e32 v133, s5, v133
	v_lshlrev_b32_e32 v248, 16, v134
	v_and_b32_e32 v134, s5, v134
	v_lshlrev_b32_e32 v249, 16, v135
	v_and_b32_e32 v135, s5, v135
	v_fma_f32 v116, v116, 0.5, v246
	v_fma_f32 v117, v117, 0.5, v132
	v_fma_f32 v118, v118, 0.5, v247
	v_fma_f32 v119, v119, 0.5, v133
	v_fma_f32 v112, v112, 0.5, v248
	v_fma_f32 v113, v113, 0.5, v134
	v_fma_f32 v114, v114, 0.5, v249
	v_fma_f32 v115, v115, 0.5, v135
	v_cvt_pk_bf16_f32 v132, v116, v117
	v_cvt_pk_bf16_f32 v133, v118, v119
	v_cvt_pk_bf16_f32 v134, v112, v113
	v_cvt_pk_bf16_f32 v135, v114, v115
	v_fmac_f32_e32 v124, v116, v116
	v_fmac_f32_e32 v124, v117, v117
	v_fmac_f32_e32 v124, v118, v118
	v_fmac_f32_e32 v124, v119, v119
	v_fmac_f32_e32 v124, v112, v112
	v_fmac_f32_e32 v124, v113, v113
	v_fmac_f32_e32 v124, v114, v114
	v_fmac_f32_e32 v124, v115, v115
	global_store_dwordx4 v178, v[128:131], s[0:1]
	global_store_dwordx4 v178, v[132:135], s[0:1] offset:256
	s_add_u32 s0, s0, 0x8000
	s_addc_u32 s1, s1, 0
	s_waitcnt vmcnt(14)
	v_lshlrev_b32_e32 v246, 16, v136
	v_and_b32_e32 v136, s5, v136
	v_lshlrev_b32_e32 v247, 16, v137
	v_and_b32_e32 v137, s5, v137
	v_lshlrev_b32_e32 v248, 16, v138
	v_and_b32_e32 v138, s5, v138
	v_lshlrev_b32_e32 v249, 16, v139
	v_and_b32_e32 v139, s5, v139
	v_fma_f32 v108, v108, 0.5, v246
	v_fma_f32 v109, v109, 0.5, v136
	v_fma_f32 v110, v110, 0.5, v247
	v_fma_f32 v111, v111, 0.5, v137
	v_fma_f32 v104, v104, 0.5, v248
	v_fma_f32 v105, v105, 0.5, v138
	v_fma_f32 v106, v106, 0.5, v249
	v_fma_f32 v107, v107, 0.5, v139
	v_cvt_pk_bf16_f32 v136, v108, v109
	v_cvt_pk_bf16_f32 v137, v110, v111
	v_cvt_pk_bf16_f32 v138, v104, v105
	v_cvt_pk_bf16_f32 v139, v106, v107
	v_mul_f32_e32 v108, v108, v108
	v_fmac_f32_e32 v108, v109, v109
	v_fmac_f32_e32 v108, v110, v110
	v_fmac_f32_e32 v108, v111, v111
	v_fmac_f32_e32 v108, v104, v104
	v_fmac_f32_e32 v108, v105, v105
	v_fmac_f32_e32 v108, v106, v106
	v_fmac_f32_e32 v108, v107, v107
	v_lshlrev_b32_e32 v246, 16, v140
	v_and_b32_e32 v140, s5, v140
	v_lshlrev_b32_e32 v247, 16, v141
	v_and_b32_e32 v141, s5, v141
	v_lshlrev_b32_e32 v248, 16, v142
	v_and_b32_e32 v142, s5, v142
	v_lshlrev_b32_e32 v249, 16, v143
	v_and_b32_e32 v143, s5, v143
	v_fma_f32 v100, v100, 0.5, v246
	v_fma_f32 v101, v101, 0.5, v140
	v_fma_f32 v102, v102, 0.5, v247
	v_fma_f32 v103, v103, 0.5, v141
	v_fma_f32 v96, v96, 0.5, v248
	v_fma_f32 v97, v97, 0.5, v142
	v_fma_f32 v98, v98, 0.5, v249
	v_fma_f32 v99, v99, 0.5, v143
	v_cvt_pk_bf16_f32 v140, v100, v101
	v_cvt_pk_bf16_f32 v141, v102, v103
	v_cvt_pk_bf16_f32 v142, v96, v97
	v_cvt_pk_bf16_f32 v143, v98, v99
	v_fmac_f32_e32 v108, v100, v100
	v_fmac_f32_e32 v108, v101, v101
	v_fmac_f32_e32 v108, v102, v102
	v_fmac_f32_e32 v108, v103, v103
	v_fmac_f32_e32 v108, v96, v96
	v_fmac_f32_e32 v108, v97, v97
	v_fmac_f32_e32 v108, v98, v98
	v_fmac_f32_e32 v108, v99, v99
	global_store_dwordx4 v178, v[136:139], s[0:1]
	global_store_dwordx4 v178, v[140:143], s[0:1] offset:256
	s_add_u32 s0, s0, 0x8000
	s_addc_u32 s1, s1, 0
	s_waitcnt vmcnt(14)
; __device__ __forceinline__ u32x4 pack8(const f32x4& a, const f32x4& b) { u32x4 w; w.x = cvt_pk_bf16(a[0], a[1]); w.y = cvt_pk_bf16(a[2], a[3]); w.z = cvt_pk_bf16(b[0], b[1]); w.w = cvt_pk_bf16(b[2], b[3]); return w; }
;     __device__ __forceinline__ void operator()(const f32x4 (&acc)[2][2][4][2], const Unit& u, int ui, int wr, int wc, int fr, int fq) const {
;     ...
;             for (int m = 0; m < 4; ++m) { const int row = row0 + ai * HALF + m * 16; const size_t off = (size_t)row * 1024 + col0; float q = 0.f;
;                 f32x4 v[2][2];
;                 if (basef) {
; #pragma unroll
;                     for (int bj = 0; bj < 2; ++bj) { v[bj][0] = *(const f32x4*)(basef + off + bj * HALF); v[bj][1] = *(const f32x4*)(basef + off + bj * HALF + 4); }
;                 } else {
; #pragma unroll
;                     for (int bj = 0; bj < 2; ++bj) { const u32x4 raw = *(const u32x4*)(xb + off + bj * HALF);
;                         v[bj][0] = (f32x4){__builtin_bit_cast(float, raw.x << 16), __builtin_bit_cast(float, raw.x & 0xffff0000u), __builtin_bit_cast(float, raw.y << 16), __builtin_bit_cast(float, raw.y & 0xffff0000u)};
;                         v[bj][1] = (f32x4){__builtin_bit_cast(float, raw.z << 16), __builtin_bit_cast(float, raw.z & 0xffff0000u), __builtin_bit_cast(float, raw.w << 16), __builtin_bit_cast(float, raw.w & 0xffff0000u)}; }
;                 }
; #pragma unroll
;                 for (int bj = 0; bj < 2; ++bj) {
;                     f32x4 v0 = v[bj][0] + acc[ai][bj][m][0] * alpha, v1 = v[bj][1] + acc[ai][bj][m][1] * alpha;
;                     if (HAS_BIAS) { v0 += bv[bj][0]; v1 += bv[bj][1]; }
;                     if (outf) { *(f32x4*)(outf + off + bj * HALF) = v0; *(f32x4*)(outf + off + bj * HALF + 4) = v1; }
;                     else *(u32x4*)(xb + off + bj * HALF) = pack8(v0, v1);
;                     q += (v0[0] * v0[0] + v0[1] * v0[1]) + (v0[2] * v0[2] + v0[3] * v0[3]) + (v1[0] * v1[0] + v1[1] * v1[1]) + (v1[2] * v1[2] + v1[3] * v1[3]); }
	v_lshlrev_b32_e32 v246, 16, v174
	v_and_b32_e32 v174, s5, v174
	v_lshlrev_b32_e32 v247, 16, v175
	v_and_b32_e32 v175, s5, v175
	v_lshlrev_b32_e32 v248, 16, v176
	v_and_b32_e32 v176, s5, v176
	v_lshlrev_b32_e32 v249, 16, v177
	v_and_b32_e32 v177, s5, v177
	v_fma_f32 v92, v92, 0.5, v246
	v_fma_f32 v93, v93, 0.5, v174
	v_fma_f32 v94, v94, 0.5, v247
	v_fma_f32 v95, v95, 0.5, v175
	v_fma_f32 v88, v88, 0.5, v248
	v_fma_f32 v89, v89, 0.5, v176
	v_fma_f32 v90, v90, 0.5, v249
	v_fma_f32 v91, v91, 0.5, v177
	v_cvt_pk_bf16_f32 v174, v92, v93
	v_cvt_pk_bf16_f32 v175, v94, v95
	v_cvt_pk_bf16_f32 v176, v88, v89
	v_cvt_pk_bf16_f32 v177, v90, v91
	v_mul_f32_e32 v92, v92, v92
	v_fmac_f32_e32 v92, v93, v93
	v_fmac_f32_e32 v92, v94, v94
	v_fmac_f32_e32 v92, v95, v95
	v_fmac_f32_e32 v92, v88, v88
	v_fmac_f32_e32 v92, v89, v89
	v_fmac_f32_e32 v92, v90, v90
	v_fmac_f32_e32 v92, v91, v91
	v_lshlrev_b32_e32 v246, 16, v184
	v_and_b32_e32 v184, s5, v184
	v_lshlrev_b32_e32 v247, 16, v185
	v_and_b32_e32 v185, s5, v185
	v_lshlrev_b32_e32 v248, 16, v186
	v_and_b32_e32 v186, s5, v186
	v_lshlrev_b32_e32 v249, 16, v187
	v_and_b32_e32 v187, s5, v187
	v_fma_f32 v84, v84, 0.5, v246
	v_fma_f32 v85, v85, 0.5, v184
	v_fma_f32 v86, v86, 0.5, v247
	v_fma_f32 v87, v87, 0.5, v185
	v_fma_f32 v80, v80, 0.5, v248
	v_fma_f32 v81, v81, 0.5, v186
	v_fma_f32 v82, v82, 0.5, v249
	v_fma_f32 v83, v83, 0.5, v187
	v_cvt_pk_bf16_f32 v184, v84, v85
	v_cvt_pk_bf16_f32 v185, v86, v87
	v_cvt_pk_bf16_f32 v186, v80, v81
	v_cvt_pk_bf16_f32 v187, v82, v83
	v_fmac_f32_e32 v92, v84, v84
	v_fmac_f32_e32 v92, v85, v85
	v_fmac_f32_e32 v92, v86, v86
	v_fmac_f32_e32 v92, v87, v87
	v_fmac_f32_e32 v92, v80, v80
	v_fmac_f32_e32 v92, v81, v81
	v_fmac_f32_e32 v92, v82, v82
	v_fmac_f32_e32 v92, v83, v83
	global_store_dwordx4 v178, v[174:177], s[0:1]
	global_store_dwordx4 v178, v[184:187], s[0:1] offset:256
	s_add_u32 s0, s0, 0x8000
	s_addc_u32 s1, s1, 0
	s_waitcnt vmcnt(14)
	v_lshlrev_b32_e32 v246, 16, v188
	v_and_b32_e32 v188, s5, v188
	v_lshlrev_b32_e32 v247, 16, v189
	v_and_b32_e32 v189, s5, v189
	v_lshlrev_b32_e32 v248, 16, v190
	v_and_b32_e32 v190, s5, v190
	v_lshlrev_b32_e32 v249, 16, v191
	v_and_b32_e32 v191, s5, v191
	v_fma_f32 v76, v76, 0.5, v246
	v_fma_f32 v77, v77, 0.5, v188
	v_fma_f32 v78, v78, 0.5, v247
	v_fma_f32 v79, v79, 0.5, v189
	v_fma_f32 v72, v72, 0.5, v248
	v_fma_f32 v73, v73, 0.5, v190
	v_fma_f32 v74, v74, 0.5, v249
	v_fma_f32 v75, v75, 0.5, v191
	v_cvt_pk_bf16_f32 v188, v76, v77
	v_cvt_pk_bf16_f32 v189, v78, v79
	v_cvt_pk_bf16_f32 v190, v72, v73
	v_cvt_pk_bf16_f32 v191, v74, v75
	v_mul_f32_e32 v76, v76, v76
	v_fmac_f32_e32 v76, v77, v77
	v_fmac_f32_e32 v76, v78, v78
	v_fmac_f32_e32 v76, v79, v79
	v_fmac_f32_e32 v76, v72, v72
	v_fmac_f32_e32 v76, v73, v73
	v_fmac_f32_e32 v76, v74, v74
	v_fmac_f32_e32 v76, v75, v75
	v_lshlrev_b32_e32 v246, 16, v208
	v_and_b32_e32 v208, s5, v208
	v_lshlrev_b32_e32 v247, 16, v209
	v_and_b32_e32 v209, s5, v209
	v_lshlrev_b32_e32 v248, 16, v210
	v_and_b32_e32 v210, s5, v210
	v_lshlrev_b32_e32 v249, 16, v211
	v_and_b32_e32 v211, s5, v211
	v_fma_f32 v68, v68, 0.5, v246
	v_fma_f32 v69, v69, 0.5, v208
	v_fma_f32 v70, v70, 0.5, v247
	v_fma_f32 v71, v71, 0.5, v209
	v_fma_f32 v64, v64, 0.5, v248
	v_fma_f32 v65, v65, 0.5, v210
	v_fma_f32 v66, v66, 0.5, v249
	v_fma_f32 v67, v67, 0.5, v211
	v_cvt_pk_bf16_f32 v208, v68, v69
	v_cvt_pk_bf16_f32 v209, v70, v71
	v_cvt_pk_bf16_f32 v210, v64, v65
	v_cvt_pk_bf16_f32 v211, v66, v67
	v_fmac_f32_e32 v76, v68, v68
	v_fmac_f32_e32 v76, v69, v69
	v_fmac_f32_e32 v76, v70, v70
	v_fmac_f32_e32 v76, v71, v71
	v_fmac_f32_e32 v76, v64, v64
	v_fmac_f32_e32 v76, v65, v65
	v_fmac_f32_e32 v76, v66, v66
	v_fmac_f32_e32 v76, v67, v67
	global_store_dwordx4 v178, v[188:191], s[0:1]
	global_store_dwordx4 v178, v[208:211], s[0:1] offset:256
	s_add_u32 s0, s0, 0x28000
	s_addc_u32 s1, s1, 0
	s_waitcnt vmcnt(14)
	v_lshlrev_b32_e32 v246, 16, v212
	v_and_b32_e32 v212, s5, v212
	v_lshlrev_b32_e32 v247, 16, v213
	v_and_b32_e32 v213, s5, v213
	v_lshlrev_b32_e32 v248, 16, v214
	v_and_b32_e32 v214, s5, v214
	v_lshlrev_b32_e32 v249, 16, v215
	v_and_b32_e32 v215, s5, v215
	v_fma_f32 v60, v60, 0.5, v246
	v_fma_f32 v61, v61, 0.5, v212
	v_fma_f32 v62, v62, 0.5, v247
	v_fma_f32 v63, v63, 0.5, v213
	v_fma_f32 v56, v56, 0.5, v248
	v_fma_f32 v57, v57, 0.5, v214
	v_fma_f32 v58, v58, 0.5, v249
	v_fma_f32 v59, v59, 0.5, v215
	v_cvt_pk_bf16_f32 v212, v60, v61
	v_cvt_pk_bf16_f32 v213, v62, v63
	v_cvt_pk_bf16_f32 v214, v56, v57
	v_cvt_pk_bf16_f32 v215, v58, v59
	v_mul_f32_e32 v60, v60, v60
	v_fmac_f32_e32 v60, v61, v61
	v_fmac_f32_e32 v60, v62, v62
	v_fmac_f32_e32 v60, v63, v63
	v_fmac_f32_e32 v60, v56, v56
	v_fmac_f32_e32 v60, v57, v57
	v_fmac_f32_e32 v60, v58, v58
	v_fmac_f32_e32 v60, v59, v59
	v_lshlrev_b32_e32 v246, 16, v216
	v_and_b32_e32 v216, s5, v216
	v_lshlrev_b32_e32 v247, 16, v217
	v_and_b32_e32 v217, s5, v217
	v_lshlrev_b32_e32 v248, 16, v218
	v_and_b32_e32 v218, s5, v218
	v_lshlrev_b32_e32 v249, 16, v219
	v_and_b32_e32 v219, s5, v219
	v_fma_f32 v52, v52, 0.5, v246
	v_fma_f32 v53, v53, 0.5, v216
	v_fma_f32 v54, v54, 0.5, v247
	v_fma_f32 v55, v55, 0.5, v217
	v_fma_f32 v48, v48, 0.5, v248
	v_fma_f32 v49, v49, 0.5, v218
	v_fma_f32 v50, v50, 0.5, v249
	v_fma_f32 v51, v51, 0.5, v219
	v_cvt_pk_bf16_f32 v216, v52, v53
	v_cvt_pk_bf16_f32 v217, v54, v55
	v_cvt_pk_bf16_f32 v218, v48, v49
	v_cvt_pk_bf16_f32 v219, v50, v51
	v_fmac_f32_e32 v60, v52, v52
	v_fmac_f32_e32 v60, v53, v53
	v_fmac_f32_e32 v60, v54, v54
	v_fmac_f32_e32 v60, v55, v55
	v_fmac_f32_e32 v60, v48, v48
	v_fmac_f32_e32 v60, v49, v49
	v_fmac_f32_e32 v60, v50, v50
	v_fmac_f32_e32 v60, v51, v51
	global_store_dwordx4 v178, v[212:215], s[0:1]
	global_store_dwordx4 v178, v[216:219], s[0:1] offset:256
	s_add_u32 s0, s0, 0x8000
	s_addc_u32 s1, s1, 0
	s_waitcnt vmcnt(14)
; __device__ __forceinline__ u32x4 pack8(const f32x4& a, const f32x4& b) { u32x4 w; w.x = cvt_pk_bf16(a[0], a[1]); w.y = cvt_pk_bf16(a[2], a[3]); w.z = cvt_pk_bf16(b[0], b[1]); w.w = cvt_pk_bf16(b[2], b[3]); return w; }
;     __device__ __forceinline__ void operator()(const f32x4 (&acc)[2][2][4][2], const Unit& u, int ui, int wr, int wc, int fr, int fq) const {
;     ...
;             for (int m = 0; m < 4; ++m) { const int row = row0 + ai * HALF + m * 16; const size_t off = (size_t)row * 1024 + col0; float q = 0.f;
;                 f32x4 v[2][2];
;                 if (basef) {
; #pragma unroll
;                     for (int bj = 0; bj < 2; ++bj) { v[bj][0] = *(const f32x4*)(basef + off + bj * HALF); v[bj][1] = *(const f32x4*)(basef + off + bj * HALF + 4); }
;                 } else {
; #pragma unroll
;                     for (int bj = 0; bj < 2; ++bj) { const u32x4 raw = *(const u32x4*)(xb + off + bj * HALF);
;                         v[bj][0] = (f32x4){__builtin_bit_cast(float, raw.x << 16), __builtin_bit_cast(float, raw.x & 0xffff0000u), __builtin_bit_cast(float, raw.y << 16), __builtin_bit_cast(float, raw.y & 0xffff0000u)};
;                         v[bj][1] = (f32x4){__builtin_bit_cast(float, raw.z << 16), __builtin_bit_cast(float, raw.z & 0xffff0000u), __builtin_bit_cast(float, raw.w << 16), __builtin_bit_cast(float, raw.w & 0xffff0000u)}; }
;                 }
; #pragma unroll
;                 for (int bj = 0; bj < 2; ++bj) {
;                     f32x4 v0 = v[bj][0] + acc[ai][bj][m][0] * alpha, v1 = v[bj][1] + acc[ai][bj][m][1] * alpha;
;                     if (HAS_BIAS) { v0 += bv[bj][0]; v1 += bv[bj][1]; }
;                     if (outf) { *(f32x4*)(outf + off + bj * HALF) = v0; *(f32x4*)(outf + off + bj * HALF + 4) = v1; }
;                     else *(u32x4*)(xb + off + bj * HALF) = pack8(v0, v1);
;                     q += (v0[0] * v0[0] + v0[1] * v0[1]) + (v0[2] * v0[2] + v0[3] * v0[3]) + (v1[0] * v1[0] + v1[1] * v1[1]) + (v1[2] * v1[2] + v1[3] * v1[3]); }
	v_lshlrev_b32_e32 v246, 16, v220
	v_and_b32_e32 v220, s5, v220
	v_lshlrev_b32_e32 v247, 16, v221
	v_and_b32_e32 v221, s5, v221
	v_lshlrev_b32_e32 v248, 16, v222
	v_and_b32_e32 v222, s5, v222
	v_lshlrev_b32_e32 v249, 16, v223
	v_and_b32_e32 v223, s5, v223
	v_fma_f32 v44, v44, 0.5, v246
	v_fma_f32 v45, v45, 0.5, v220
	v_fma_f32 v46, v46, 0.5, v247
	v_fma_f32 v47, v47, 0.5, v221
	v_fma_f32 v40, v40, 0.5, v248
	v_fma_f32 v41, v41, 0.5, v222
	v_fma_f32 v42, v42, 0.5, v249
	v_fma_f32 v43, v43, 0.5, v223
	v_cvt_pk_bf16_f32 v220, v44, v45
	v_cvt_pk_bf16_f32 v221, v46, v47
	v_cvt_pk_bf16_f32 v222, v40, v41
	v_cvt_pk_bf16_f32 v223, v42, v43
	v_mul_f32_e32 v44, v44, v44
	v_fmac_f32_e32 v44, v45, v45
	v_fmac_f32_e32 v44, v46, v46
	v_fmac_f32_e32 v44, v47, v47
	v_fmac_f32_e32 v44, v40, v40
	v_fmac_f32_e32 v44, v41, v41
	v_fmac_f32_e32 v44, v42, v42
	v_fmac_f32_e32 v44, v43, v43
	v_lshlrev_b32_e32 v246, 16, v224
	v_and_b32_e32 v224, s5, v224
	v_lshlrev_b32_e32 v247, 16, v225
	v_and_b32_e32 v225, s5, v225
	v_lshlrev_b32_e32 v248, 16, v226
	v_and_b32_e32 v226, s5, v226
	v_lshlrev_b32_e32 v249, 16, v227
	v_and_b32_e32 v227, s5, v227
	v_fma_f32 v36, v36, 0.5, v246
	v_fma_f32 v37, v37, 0.5, v224
	v_fma_f32 v38, v38, 0.5, v247
	v_fma_f32 v39, v39, 0.5, v225
	v_fma_f32 v32, v32, 0.5, v248
	v_fma_f32 v33, v33, 0.5, v226
	v_fma_f32 v34, v34, 0.5, v249
	v_fma_f32 v35, v35, 0.5, v227
	v_cvt_pk_bf16_f32 v224, v36, v37
	v_cvt_pk_bf16_f32 v225, v38, v39
	v_cvt_pk_bf16_f32 v226, v32, v33
	v_cvt_pk_bf16_f32 v227, v34, v35
	v_fmac_f32_e32 v44, v36, v36
	v_fmac_f32_e32 v44, v37, v37
	v_fmac_f32_e32 v44, v38, v38
	v_fmac_f32_e32 v44, v39, v39
	v_fmac_f32_e32 v44, v32, v32
	v_fmac_f32_e32 v44, v33, v33
	v_fmac_f32_e32 v44, v34, v34
	v_fmac_f32_e32 v44, v35, v35
	global_store_dwordx4 v178, v[220:223], s[0:1]
	global_store_dwordx4 v178, v[224:227], s[0:1] offset:256
	s_add_u32 s0, s0, 0x8000
	s_addc_u32 s1, s1, 0
	s_waitcnt vmcnt(14)
	v_lshlrev_b32_e32 v246, 16, v230
	v_and_b32_e32 v230, s5, v230
	v_lshlrev_b32_e32 v247, 16, v231
	v_and_b32_e32 v231, s5, v231
	v_lshlrev_b32_e32 v248, 16, v232
	v_and_b32_e32 v232, s5, v232
	v_lshlrev_b32_e32 v249, 16, v233
	v_and_b32_e32 v233, s5, v233
	v_fma_f32 v28, v28, 0.5, v246
	v_fma_f32 v29, v29, 0.5, v230
	v_fma_f32 v30, v30, 0.5, v247
	v_fma_f32 v31, v31, 0.5, v231
	v_fma_f32 v24, v24, 0.5, v248
	v_fma_f32 v25, v25, 0.5, v232
	v_fma_f32 v26, v26, 0.5, v249
	v_fma_f32 v27, v27, 0.5, v233
	v_cvt_pk_bf16_f32 v230, v28, v29
	v_cvt_pk_bf16_f32 v231, v30, v31
	v_cvt_pk_bf16_f32 v232, v24, v25
	v_cvt_pk_bf16_f32 v233, v26, v27
	v_mul_f32_e32 v28, v28, v28
	v_fmac_f32_e32 v28, v29, v29
	v_fmac_f32_e32 v28, v30, v30
	v_fmac_f32_e32 v28, v31, v31
	v_fmac_f32_e32 v28, v24, v24
	v_fmac_f32_e32 v28, v25, v25
	v_fmac_f32_e32 v28, v26, v26
	v_fmac_f32_e32 v28, v27, v27
	v_lshlrev_b32_e32 v246, 16, v234
	v_and_b32_e32 v234, s5, v234
	v_lshlrev_b32_e32 v247, 16, v235
	v_and_b32_e32 v235, s5, v235
	v_lshlrev_b32_e32 v248, 16, v236
	v_and_b32_e32 v236, s5, v236
	v_lshlrev_b32_e32 v249, 16, v237
	v_and_b32_e32 v237, s5, v237
	v_fma_f32 v20, v20, 0.5, v246
	v_fma_f32 v21, v21, 0.5, v234
	v_fma_f32 v22, v22, 0.5, v247
	v_fma_f32 v23, v23, 0.5, v235
	v_fma_f32 v16, v16, 0.5, v248
	v_fma_f32 v17, v17, 0.5, v236
	v_fma_f32 v18, v18, 0.5, v249
	v_fma_f32 v19, v19, 0.5, v237
	v_cvt_pk_bf16_f32 v234, v20, v21
	v_cvt_pk_bf16_f32 v235, v22, v23
	v_cvt_pk_bf16_f32 v236, v16, v17
	v_cvt_pk_bf16_f32 v237, v18, v19
	v_fmac_f32_e32 v28, v20, v20
	v_fmac_f32_e32 v28, v21, v21
	v_fmac_f32_e32 v28, v22, v22
	v_fmac_f32_e32 v28, v23, v23
	v_fmac_f32_e32 v28, v16, v16
	v_fmac_f32_e32 v28, v17, v17
	v_fmac_f32_e32 v28, v18, v18
	v_fmac_f32_e32 v28, v19, v19
	global_store_dwordx4 v178, v[230:233], s[0:1]
	global_store_dwordx4 v178, v[234:237], s[0:1] offset:256
	s_add_u32 s0, s0, 0x8000
	s_addc_u32 s1, s1, 0
	s_waitcnt vmcnt(14)
; __device__ __forceinline__ u32x4 pack8(const f32x4& a, const f32x4& b) { u32x4 w; w.x = cvt_pk_bf16(a[0], a[1]); w.y = cvt_pk_bf16(a[2], a[3]); w.z = cvt_pk_bf16(b[0], b[1]); w.w = cvt_pk_bf16(b[2], b[3]); return w; }
;     __device__ __forceinline__ void operator()(const f32x4 (&acc)[2][2][4][2], const Unit& u, int ui, int wr, int wc, int fr, int fq) const {
;     ...
;             for (int m = 0; m < 4; ++m) { const int row = row0 + ai * HALF + m * 16; const size_t off = (size_t)row * 1024 + col0; float q = 0.f;
;                 f32x4 v[2][2];
;                 if (basef) {
; #pragma unroll
;                     for (int bj = 0; bj < 2; ++bj) { v[bj][0] = *(const f32x4*)(basef + off + bj * HALF); v[bj][1] = *(const f32x4*)(basef + off + bj * HALF + 4); }
;                 } else {
; #pragma unroll
;                     for (int bj = 0; bj < 2; ++bj) { const u32x4 raw = *(const u32x4*)(xb + off + bj * HALF);
;                         v[bj][0] = (f32x4){__builtin_bit_cast(float, raw.x << 16), __builtin_bit_cast(float, raw.x & 0xffff0000u), __builtin_bit_cast(float, raw.y << 16), __builtin_bit_cast(float, raw.y & 0xffff0000u)};
;                         v[bj][1] = (f32x4){__builtin_bit_cast(float, raw.z << 16), __builtin_bit_cast(float, raw.z & 0xffff0000u), __builtin_bit_cast(float, raw.w << 16), __builtin_bit_cast(float, raw.w & 0xffff0000u)}; }
;                 }
; #pragma unroll
;                 for (int bj = 0; bj < 2; ++bj) {
;                     f32x4 v0 = v[bj][0] + acc[ai][bj][m][0] * alpha, v1 = v[bj][1] + acc[ai][bj][m][1] * alpha;
;                     if (HAS_BIAS) { v0 += bv[bj][0]; v1 += bv[bj][1]; }
;                     if (outf) { *(f32x4*)(outf + off + bj * HALF) = v0; *(f32x4*)(outf + off + bj * HALF + 4) = v1; }
;                     else *(u32x4*)(xb + off + bj * HALF) = pack8(v0, v1);
;                     q += (v0[0] * v0[0] + v0[1] * v0[1]) + (v0[2] * v0[2] + v0[3] * v0[3]) + (v1[0] * v1[0] + v1[1] * v1[1]) + (v1[2] * v1[2] + v1[3] * v1[3]); }
;                 q += __shfl_xor(q, 16); q += __shfl_xor(q, 32);
;                 if (fq == 0) ssp[(size_t)row * 16 + u.pn * 4 + wc] = q;
	v_lshlrev_b32_e32 v246, 16, v238
	v_and_b32_e32 v238, s5, v238
	v_lshlrev_b32_e32 v247, 16, v239
	v_and_b32_e32 v239, s5, v239
	v_lshlrev_b32_e32 v248, 16, v240
	v_and_b32_e32 v240, s5, v240
	v_lshlrev_b32_e32 v249, 16, v241
	v_and_b32_e32 v241, s5, v241
	v_fma_f32 v12, v12, 0.5, v246
	v_fma_f32 v13, v13, 0.5, v238
	v_fma_f32 v14, v14, 0.5, v247
	v_fma_f32 v15, v15, 0.5, v239
	v_fma_f32 v8, v8, 0.5, v248
	v_fma_f32 v9, v9, 0.5, v240
	v_fma_f32 v10, v10, 0.5, v249
	v_fma_f32 v11, v11, 0.5, v241
	v_cvt_pk_bf16_f32 v238, v12, v13
	v_cvt_pk_bf16_f32 v239, v14, v15
	v_cvt_pk_bf16_f32 v240, v8, v9
	v_cvt_pk_bf16_f32 v241, v10, v11
	v_mul_f32_e32 v12, v12, v12
	v_fmac_f32_e32 v12, v13, v13
	v_fmac_f32_e32 v12, v14, v14
	v_fmac_f32_e32 v12, v15, v15
	v_fmac_f32_e32 v12, v8, v8
	v_fmac_f32_e32 v12, v9, v9
	v_fmac_f32_e32 v12, v10, v10
	v_fmac_f32_e32 v12, v11, v11
	v_lshlrev_b32_e32 v246, 16, v242
	v_and_b32_e32 v242, s5, v242
	v_lshlrev_b32_e32 v247, 16, v243
	v_and_b32_e32 v243, s5, v243
	v_lshlrev_b32_e32 v248, 16, v244
	v_and_b32_e32 v244, s5, v244
	v_lshlrev_b32_e32 v249, 16, v245
	v_and_b32_e32 v245, s5, v245
	v_fma_f32 v4, v4, 0.5, v246
	v_fma_f32 v5, v5, 0.5, v242
	v_fma_f32 v6, v6, 0.5, v247
	v_fma_f32 v7, v7, 0.5, v243
	v_fma_f32 v0, v0, 0.5, v248
	v_fma_f32 v1, v1, 0.5, v244
	v_fma_f32 v2, v2, 0.5, v249
	v_fma_f32 v3, v3, 0.5, v245
	v_cvt_pk_bf16_f32 v242, v4, v5
	v_cvt_pk_bf16_f32 v243, v6, v7
	v_cvt_pk_bf16_f32 v244, v0, v1
	v_cvt_pk_bf16_f32 v245, v2, v3
	v_fmac_f32_e32 v12, v4, v4
	v_fmac_f32_e32 v12, v5, v5
	v_fmac_f32_e32 v12, v6, v6
	v_fmac_f32_e32 v12, v7, v7
	v_fmac_f32_e32 v12, v0, v0
	v_fmac_f32_e32 v12, v1, v1
	v_fmac_f32_e32 v12, v2, v2
	v_fmac_f32_e32 v12, v3, v3
	global_store_dwordx4 v178, v[238:241], s[0:1]
	global_store_dwordx4 v178, v[242:245], s[0:1] offset:256
	ds_bpermute_b32 v128, v183, v124
	ds_bpermute_b32 v129, v183, v108
	ds_bpermute_b32 v130, v183, v92
	ds_bpermute_b32 v131, v183, v76
	ds_bpermute_b32 v132, v183, v60
	ds_bpermute_b32 v133, v183, v44
	ds_bpermute_b32 v134, v183, v28
	ds_bpermute_b32 v135, v183, v12
	s_waitcnt lgkmcnt(0)
	v_add_f32_e32 v124, v124, v128
	v_add_f32_e32 v108, v108, v129
	v_add_f32_e32 v92, v92, v130
	v_add_f32_e32 v76, v76, v131
	v_add_f32_e32 v60, v60, v132
	v_add_f32_e32 v44, v44, v133
	v_add_f32_e32 v28, v28, v134
	v_add_f32_e32 v12, v12, v135
	ds_bpermute_b32 v128, v228, v124
	ds_bpermute_b32 v129, v228, v108
	ds_bpermute_b32 v130, v228, v92
	ds_bpermute_b32 v131, v228, v76
	ds_bpermute_b32 v132, v228, v60
	ds_bpermute_b32 v133, v228, v44
	ds_bpermute_b32 v134, v228, v28
	ds_bpermute_b32 v135, v228, v12
	s_waitcnt lgkmcnt(0)
	v_add_f32_e32 v124, v124, v128
	v_add_f32_e32 v108, v108, v129
	v_add_f32_e32 v92, v92, v130
	v_add_f32_e32 v76, v76, v131
	v_add_f32_e32 v60, v60, v132
	v_add_f32_e32 v44, v44, v133
	v_add_f32_e32 v28, v28, v134
	v_add_f32_e32 v12, v12, v135
	s_mov_b64 exec, 0xffff
	global_store_dword v179, v124, s[2:3]
	s_add_u32 s2, s2, 0x400
	s_addc_u32 s3, s3, 0
	global_store_dword v179, v108, s[2:3]
	s_add_u32 s2, s2, 0x400
	s_addc_u32 s3, s3, 0
	global_store_dword v179, v92, s[2:3]
	s_add_u32 s2, s2, 0x400
	s_addc_u32 s3, s3, 0
	global_store_dword v179, v76, s[2:3]
	s_add_u32 s2, s2, 0x1400
	s_addc_u32 s3, s3, 0
	global_store_dword v179, v60, s[2:3]
	s_add_u32 s2, s2, 0x400
	s_addc_u32 s3, s3, 0
	global_store_dword v179, v44, s[2:3]
	s_add_u32 s2, s2, 0x400
	s_addc_u32 s3, s3, 0
	global_store_dword v179, v28, s[2:3]
	s_add_u32 s2, s2, 0x400
	s_addc_u32 s3, s3, 0
	global_store_dword v179, v12, s[2:3]
	s_mov_b64 exec, -1
	s_branch .Ldn_epi_done
